# prompt attention QK^T segment: K fragment ds_reads issued three fragments ahead over three buffers with counted lgkmcnt waits (plus partialSM between P.V MFMAs, counted waits there)
# baseline (speedup 1.0000x reference)
.LBB0_1167:
	ds_read_b128 v[80:83], v189
	ds_read_b128 v[84:87], v189 offset:32
	ds_read_b128 v[64:67], v189 offset:128
	ds_read_b128 v[68:71], v189 offset:160
	ds_read_b128 v[88:91], v189 offset:64
	ds_read_b128 v[72:75], v189 offset:192
	ds_read_b128 v[92:95], v189 offset:96
	ds_read_b128 v[76:79], v189 offset:224
	ds_read_b128 v[210:213], v181 offset:49152
	ds_read_b128 v[206:209], v181 offset:57344
	ds_read_b128 v[242:245], v182 offset:49152
	v_add_f32_e32 v146, 0, v147
	v_add_f32_e32 v146, v148, v146
	v_add_f32_e32 v146, v149, v146
	s_waitcnt lgkmcnt(2)
	v_mfma_f32_32x32x16_bf16 v[80:95], v[210:213], v[126:129], v[80:95]
	ds_read_b128 v[210:213], v182 offset:57344
	v_add_f32_e32 v146, v202, v146
	v_add_f32_e32 v146, v203, v146
	v_add_f32_e32 v146, v205, v146
	v_add_f32_e32 v146, v201, v146
	v_add_f32_e32 v146, v204, v146
	v_add_f32_e32 v146, v193, v146
	v_add_f32_e32 v146, v195, v146
	s_waitcnt lgkmcnt(2)
	v_mfma_f32_32x32x16_bf16 v[64:79], v[206:209], v[126:129], v[64:79]
	ds_read_b128 v[206:209], v180 offset:49152
	v_add_f32_e32 v146, v196, v146
	v_add_f32_e32 v146, v199, v146
	v_exp_f32_e32 v142, v142
	v_add_f32_e32 v146, v194, v146
	v_exp_f32_e32 v143, v143
	v_add_f32_e32 v146, v197, v146
	s_waitcnt lgkmcnt(2)
	v_mfma_f32_32x32x16_bf16 v[80:95], v[242:245], v[122:125], v[80:95]
	ds_read_b128 v[242:245], v180 offset:57344
	v_exp_f32_e32 v140, v140
	v_add_f32_e32 v146, v198, v146
	v_exp_f32_e32 v141, v141
	v_add_f32_e32 v146, v200, v146
	v_exp_f32_e32 v136, v136
	v_add_f32_e32 v146, v142, v146
	v_exp_f32_e32 v137, v137
	s_waitcnt lgkmcnt(2)
	v_mfma_f32_32x32x16_bf16 v[64:79], v[210:213], v[122:125], v[64:79]
	ds_read_b128 v[210:213], v151 offset:49152
	v_add_f32_e32 v146, v143, v146
	v_exp_f32_e32 v134, v134
	v_add_f32_e32 v146, v140, v146
	v_exp_f32_e32 v135, v135
	v_add_f32_e32 v146, v141, v146
	v_exp_f32_e32 v130, v130
	s_waitcnt lgkmcnt(2)
	v_mfma_f32_32x32x16_bf16 v[80:95], v[206:209], v[118:121], v[80:95]
	ds_read_b128 v[206:209], v151 offset:57344
	v_add_f32_e32 v146, v136, v146
	v_exp_f32_e32 v131, v131
	v_add_f32_e32 v146, v137, v146
	v_exp_f32_e32 v144, v144
	v_add_f32_e32 v146, v134, v146
	v_exp_f32_e32 v145, v145
	v_add_f32_e32 v146, v135, v146
	s_waitcnt lgkmcnt(2)
	v_mfma_f32_32x32x16_bf16 v[64:79], v[242:245], v[118:121], v[64:79]
	ds_read_b128 v[242:245], v181 offset:49280
	v_exp_f32_e32 v138, v138
	v_add_f32_e32 v146, v130, v146
	v_exp_f32_e32 v139, v139
	v_add_f32_e32 v146, v131, v146
	v_exp_f32_e32 v132, v132
	v_add_f32_e32 v146, v144, v146
	s_waitcnt lgkmcnt(2)
	v_mfma_f32_32x32x16_bf16 v[80:95], v[210:213], v[114:117], v[80:95]
	ds_read_b128 v[210:213], v181 offset:57472
	v_exp_f32_e32 v133, v133
	v_add_f32_e32 v146, v145, v146
	v_add_f32_e32 v146, v138, v146
	v_add_f32_e32 v146, v139, v146
	v_add_f32_e32 v146, v132, v146
	v_add_f32_e32 v190, v133, v146
	v_mov_b32_e32 v191, v190
	s_waitcnt lgkmcnt(2)
	v_mfma_f32_32x32x16_bf16 v[64:79], v[206:209], v[114:117], v[64:79]
	ds_read_b128 v[206:209], v182 offset:49280
	v_permlane32_swap_b32_e32 v190, v191
	v_cvt_pk_bf16_f32 v146, v147, v148
	v_cvt_pk_bf16_f32 v147, v149, v202
	v_cvt_pk_bf16_f32 v148, v203, v205
	v_cvt_pk_bf16_f32 v149, v201, v204
	s_waitcnt lgkmcnt(2)
	v_mfma_f32_32x32x16_bf16 v[80:95], v[242:245], v[110:113], v[80:95]
	ds_read_b128 v[242:245], v182 offset:57472
	v_cvt_pk_bf16_f32 v192, v193, v195
	v_cvt_pk_bf16_f32 v193, v196, v199
	v_cvt_pk_bf16_f32 v194, v194, v197
	v_cvt_pk_bf16_f32 v195, v198, v200
	v_cvt_pk_bf16_f32 v196, v142, v143
	v_cvt_pk_bf16_f32 v197, v140, v141
	v_cvt_pk_bf16_f32 v198, v136, v137
	s_waitcnt lgkmcnt(2)
	v_mfma_f32_32x32x16_bf16 v[64:79], v[210:213], v[110:113], v[64:79]
	ds_read_b128 v[210:213], v180 offset:49280
	v_cvt_pk_bf16_f32 v199, v134, v135
	v_cvt_pk_bf16_f32 v200, v130, v131
	v_cvt_pk_bf16_f32 v201, v144, v145
	v_cvt_pk_bf16_f32 v202, v138, v139
	v_cvt_pk_bf16_f32 v203, v132, v133
	v_permlane32_swap_b32_e32 v146, v148
	s_waitcnt lgkmcnt(2)
	v_mfma_f32_32x32x16_bf16 v[80:95], v[206:209], v[106:109], v[80:95]
	ds_read_b128 v[206:209], v180 offset:57472
	v_permlane32_swap_b32_e32 v147, v149
	v_permlane32_swap_b32_e32 v192, v194
	v_permlane32_swap_b32_e32 v193, v195
	v_permlane32_swap_b32_e32 v196, v198
	s_waitcnt lgkmcnt(2)
	v_mfma_f32_32x32x16_bf16 v[64:79], v[242:245], v[106:109], v[64:79]
	ds_read_b128 v[242:245], v151 offset:49280
	v_permlane32_swap_b32_e32 v197, v199
	v_permlane32_swap_b32_e32 v200, v202
	v_permlane32_swap_b32_e32 v201, v203
	s_waitcnt lgkmcnt(2)
	v_mfma_f32_32x32x16_bf16 v[80:95], v[210:213], v[102:105], v[80:95]
	ds_read_b128 v[210:213], v151 offset:57472
	s_waitcnt lgkmcnt(2)
	v_mfma_f32_32x32x16_bf16 v[64:79], v[206:209], v[102:105], v[64:79]
	s_waitcnt lgkmcnt(1)
	v_mfma_f32_32x32x16_bf16 v[80:95], v[242:245], v[98:101], v[80:95]
	s_waitcnt lgkmcnt(0)
	v_mfma_f32_32x32x16_bf16 v[64:79], v[210:213], v[98:101], v[64:79]
	v_lshl_add_u64 v[130:131], v[156:157], 0, v[96:97]
	v_lshl_add_u64 v[134:135], v[152:153], 0, v[96:97]
	v_lshl_add_u64 v[138:139], v[158:159], 0, v[96:97]
	v_lshl_add_u64 v[142:143], v[154:155], 0, v[96:97]
	global_load_dwordx4 v[130:133], v[130:131], off
	s_nop 0
	global_load_dwordx4 v[134:137], v[134:135], off
	s_nop 0
	global_load_dwordx4 v[138:141], v[138:139], off
	s_nop 0
	global_load_dwordx4 v[142:145], v[142:143], off
	s_sub_i32 s6, s92, 64
	s_cmp_le_i32 s6, s41
	s_cbranch_scc0 .Lpvm_1167a
	ds_read_b64_tr_b16 v[204:205], v174 offset:0
	ds_read_b64_tr_b16 v[206:207], v174 offset:0x800
	ds_read_b64_tr_b16 v[208:209], v174 offset:0x1000
	ds_read_b64_tr_b16 v[210:211], v174 offset:0x1800
	ds_read_b64_tr_b16 v[220:221], v174 offset:0x2000
	ds_read_b64_tr_b16 v[222:223], v174 offset:0x2800
	ds_read_b64_tr_b16 v[224:225], v174 offset:0x3000
	ds_read_b64_tr_b16 v[226:227], v174 offset:0x3800
	s_nop 0
	s_waitcnt lgkmcnt(6)
	v_mfma_f32_32x32x16_bf16 v[48:63], v[146:149], v[204:207], v[48:63]
	v_max_f32_e32 v230, v81, v81
	v_max_f32_e32 v231, v80, v80
	v_max_f32_e32 v230, v231, v230
	ds_read_b64_tr_b16 v[204:205], v174 offset:0x200
	ds_read_b64_tr_b16 v[206:207], v174 offset:0xa00
	s_waitcnt lgkmcnt(6)
	v_mfma_f32_32x32x16_bf16 v[48:63], v[192:195], v[208:211], v[48:63]
	v_max3_f32 v230, v230, v82, v83
	v_max3_f32 v230, v230, v84, v85
	v_max3_f32 v230, v230, v86, v87
	ds_read_b64_tr_b16 v[208:209], v174 offset:0x1200
	ds_read_b64_tr_b16 v[210:211], v174 offset:0x1a00
	s_waitcnt lgkmcnt(6)
	v_mfma_f32_32x32x16_bf16 v[48:63], v[196:199], v[220:223], v[48:63]
	v_max3_f32 v230, v230, v88, v89
	v_max3_f32 v230, v230, v90, v91
	v_max3_f32 v230, v230, v92, v93
	ds_read_b64_tr_b16 v[220:221], v174 offset:0x2200
	ds_read_b64_tr_b16 v[222:223], v174 offset:0x2a00
	s_waitcnt lgkmcnt(6)
	v_mfma_f32_32x32x16_bf16 v[48:63], v[200:203], v[224:227], v[48:63]
	v_max3_f32 v230, v230, v94, v95
	v_max3_f32 v230, v230, v64, v65
	v_max3_f32 v230, v230, v66, v67
	ds_read_b64_tr_b16 v[224:225], v174 offset:0x3200
	ds_read_b64_tr_b16 v[226:227], v174 offset:0x3a00
	s_waitcnt lgkmcnt(6)
	v_mfma_f32_32x32x16_bf16 v[32:47], v[146:149], v[204:207], v[32:47]
	v_max3_f32 v230, v230, v68, v69
	v_max3_f32 v230, v230, v70, v71
	v_max3_f32 v230, v230, v72, v73
	ds_read_b64_tr_b16 v[204:205], v174 offset:0x400
	ds_read_b64_tr_b16 v[206:207], v174 offset:0xc00
	s_waitcnt lgkmcnt(6)
	v_mfma_f32_32x32x16_bf16 v[32:47], v[192:195], v[208:211], v[32:47]
	v_max3_f32 v230, v230, v74, v75
	v_max3_f32 v230, v230, v76, v77
	v_max3_f32 v230, v230, v78, v79
	ds_read_b64_tr_b16 v[208:209], v174 offset:0x1400
	ds_read_b64_tr_b16 v[210:211], v174 offset:0x1c00
	s_waitcnt lgkmcnt(6)
	v_mfma_f32_32x32x16_bf16 v[32:47], v[196:199], v[220:223], v[32:47]
	v_mov_b32_e32 v231, v230
	s_nop 1
	v_permlane32_swap_b32_e32 v230, v231
	ds_read_b64_tr_b16 v[220:221], v174 offset:0x2400
	ds_read_b64_tr_b16 v[222:223], v174 offset:0x2c00
	s_waitcnt lgkmcnt(6)
	v_mfma_f32_32x32x16_bf16 v[32:47], v[200:203], v[224:227], v[32:47]
	v_max_f32_e32 v231, v231, v231
	v_max_f32_e32 v230, v230, v230
	v_max_f32_e32 v230, v230, v231
	ds_read_b64_tr_b16 v[224:225], v174 offset:0x3400
	ds_read_b64_tr_b16 v[226:227], v174 offset:0x3c00
	s_waitcnt lgkmcnt(6)
	v_mfma_f32_32x32x16_bf16 v[16:31], v[146:149], v[204:207], v[16:31]
	v_sub_f32_e32 v231, v230, v187
	v_mul_f32_e32 v231, 0x3db504f3, v231
	s_mov_b32 s6, 0x41000000
	ds_read_b64_tr_b16 v[204:205], v174 offset:0x600
	ds_read_b64_tr_b16 v[206:207], v174 offset:0xe00
	s_waitcnt lgkmcnt(6)
	v_mfma_f32_32x32x16_bf16 v[16:31], v[192:195], v[208:211], v[16:31]
	v_cmp_ge_f32_e32 vcc, s6, v231
	v_max_f32_e32 v231, v187, v187
	v_max_f32_e32 v230, v231, v230
	ds_read_b64_tr_b16 v[208:209], v174 offset:0x1600
	ds_read_b64_tr_b16 v[210:211], v174 offset:0x1e00
	s_waitcnt lgkmcnt(6)
	v_mfma_f32_32x32x16_bf16 v[16:31], v[196:199], v[220:223], v[16:31]
	v_sub_f32_e32 v231, v187, v230
	v_mul_f32_e32 v231, 0x3e0293ee, v231
	v_exp_f32_e32 v231, v231
	ds_read_b64_tr_b16 v[220:221], v174 offset:0x2600
	ds_read_b64_tr_b16 v[222:223], v174 offset:0x2e00
	s_waitcnt lgkmcnt(6)
	v_mfma_f32_32x32x16_bf16 v[16:31], v[200:203], v[224:227], v[16:31]
	ds_read_b64_tr_b16 v[224:225], v174 offset:0x3600
	ds_read_b64_tr_b16 v[226:227], v174 offset:0x3e00
	s_waitcnt lgkmcnt(6)
	v_mfma_f32_32x32x16_bf16 v[0:15], v[146:149], v[204:207], v[0:15]
	s_waitcnt lgkmcnt(4)
	v_mfma_f32_32x32x16_bf16 v[0:15], v[192:195], v[208:211], v[0:15]
	s_waitcnt lgkmcnt(2)
	v_mfma_f32_32x32x16_bf16 v[0:15], v[196:199], v[220:223], v[0:15]
	s_waitcnt lgkmcnt(0)
	v_mfma_f32_32x32x16_bf16 v[0:15], v[200:203], v[224:227], v[0:15]
	s_nop 0
	v_mov_b32_e32 v146, v230
	v_mov_b32_e32 v147, v231
	s_branch .Lpvj_1167a

.LBB0_1173:
	v_cndmask_b32_e64 v187, v146, v187, s[6:7]
	v_mul_f32_e32 v146, 0xbe0293ee, v187
	v_fmamk_f32 v80, v80, 0x3e0293ee, v146
	v_fmamk_f32 v81, v81, 0x3e0293ee, v146
	v_fmamk_f32 v82, v82, 0x3e0293ee, v146
	v_fmamk_f32 v83, v83, 0x3e0293ee, v146
	v_fmamk_f32 v84, v84, 0x3e0293ee, v146
	v_fmamk_f32 v85, v85, 0x3e0293ee, v146
	v_fmamk_f32 v86, v86, 0x3e0293ee, v146
	v_fmamk_f32 v87, v87, 0x3e0293ee, v146
	v_fmamk_f32 v88, v88, 0x3e0293ee, v146
	v_fmamk_f32 v89, v89, 0x3e0293ee, v146
	v_fmamk_f32 v90, v90, 0x3e0293ee, v146
	v_fmamk_f32 v91, v91, 0x3e0293ee, v146
	v_fmamk_f32 v92, v92, 0x3e0293ee, v146
	v_fmamk_f32 v93, v93, 0x3e0293ee, v146
	v_fmamk_f32 v94, v94, 0x3e0293ee, v146
	v_fmamk_f32 v95, v95, 0x3e0293ee, v146
	v_exp_f32_e32 v139, v80
	v_exp_f32_e32 v141, v81
	v_exp_f32_e32 v142, v82
	v_exp_f32_e32 v143, v83
	v_exp_f32_e32 v144, v84
	v_exp_f32_e32 v145, v85
	v_exp_f32_e32 v138, v86
	v_exp_f32_e32 v140, v87
	v_exp_f32_e32 v133, v88
	v_exp_f32_e32 v135, v89
	v_exp_f32_e32 v136, v90
	v_exp_f32_e32 v137, v91
	v_exp_f32_e32 v130, v92
	v_exp_f32_e32 v131, v93
	v_exp_f32_e32 v132, v94
	v_exp_f32_e32 v134, v95
	v_fmamk_f32 v198, v64, 0x3e0293ee, v146
	v_fmamk_f32 v199, v65, 0x3e0293ee, v146
	v_fmamk_f32 v200, v66, 0x3e0293ee, v146
	v_fmamk_f32 v201, v67, 0x3e0293ee, v146
	v_fmamk_f32 v202, v68, 0x3e0293ee, v146
	v_fmamk_f32 v148, v69, 0x3e0293ee, v146
	v_fmamk_f32 v149, v70, 0x3e0293ee, v146
	v_fmamk_f32 v193, v71, 0x3e0293ee, v146
	v_fmamk_f32 v194, v72, 0x3e0293ee, v146
	v_fmamk_f32 v195, v73, 0x3e0293ee, v146
	v_fmamk_f32 v196, v74, 0x3e0293ee, v146
	v_fmamk_f32 v197, v75, 0x3e0293ee, v146
	v_fmamk_f32 v147, v76, 0x3e0293ee, v146
	v_fmamk_f32 v203, v77, 0x3e0293ee, v146
	v_fmamk_f32 v204, v78, 0x3e0293ee, v146
	v_fmac_f32_e32 v146, 0x3e0293ee, v79
	s_waitcnt lgkmcnt(0)
	s_barrier
	ds_read_b128 v[80:83], v189 offset:256
	ds_read_b128 v[84:87], v189 offset:288
	ds_read_b128 v[64:67], v189 offset:384
	ds_read_b128 v[68:71], v189 offset:416
	ds_read_b128 v[88:91], v189 offset:320
	ds_read_b128 v[72:75], v189 offset:448
	ds_read_b128 v[92:95], v189 offset:352
	ds_read_b128 v[76:79], v189 offset:480
	ds_read_b128 v[210:213], v181 offset:32768
	ds_read_b128 v[206:209], v181 offset:40960
	ds_read_b128 v[242:245], v182 offset:32768
	v_exp_f32_e32 v218, v146
	v_add_f32_e32 v146, 0, v139
	v_add_f32_e32 v146, v141, v146
	s_waitcnt lgkmcnt(2)
	v_mfma_f32_32x32x16_bf16 v[80:95], v[210:213], v[126:129], v[80:95]
	ds_read_b128 v[210:213], v182 offset:40960
	v_add_f32_e32 v146, v142, v146
	v_add_f32_e32 v146, v143, v146
	v_add_f32_e32 v146, v144, v146
	v_add_f32_e32 v146, v145, v146
	v_add_f32_e32 v146, v138, v146
	v_add_f32_e32 v146, v140, v146
	v_add_f32_e32 v146, v133, v146
	s_waitcnt lgkmcnt(2)
	v_mfma_f32_32x32x16_bf16 v[64:79], v[206:209], v[126:129], v[64:79]
	ds_read_b128 v[206:209], v180 offset:32768
	v_add_f32_e32 v146, v135, v146
	v_add_f32_e32 v146, v136, v146
	v_add_f32_e32 v146, v137, v146
	v_exp_f32_e32 v198, v198
	v_add_f32_e32 v146, v130, v146
	v_exp_f32_e32 v199, v199
	s_waitcnt lgkmcnt(2)
	v_mfma_f32_32x32x16_bf16 v[80:95], v[242:245], v[122:125], v[80:95]
	ds_read_b128 v[242:245], v180 offset:40960
	v_add_f32_e32 v146, v131, v146
	v_exp_f32_e32 v200, v200
	v_add_f32_e32 v146, v132, v146
	v_exp_f32_e32 v201, v201
	v_add_f32_e32 v146, v134, v146
	v_exp_f32_e32 v202, v202
	v_add_f32_e32 v146, v198, v146
	s_waitcnt lgkmcnt(2)
	v_mfma_f32_32x32x16_bf16 v[64:79], v[210:213], v[122:125], v[64:79]
	ds_read_b128 v[210:213], v151 offset:32768
	v_exp_f32_e32 v205, v148
	v_add_f32_e32 v146, v199, v146
	v_add_f32_e32 v146, v200, v146
	v_exp_f32_e32 v193, v193
	v_add_f32_e32 v146, v201, v146
	v_add_f32_e32 v146, v202, v146
	s_waitcnt lgkmcnt(2)
	v_mfma_f32_32x32x16_bf16 v[80:95], v[206:209], v[118:121], v[80:95]
	ds_read_b128 v[206:209], v151 offset:40960
	v_add_f32_e32 v146, v205, v146
	v_exp_f32_e32 v214, v203
	v_exp_f32_e32 v215, v204
	v_cvt_pk_bf16_f32 v148, v144, v145
	v_cvt_pk_bf16_f32 v198, v198, v199
	v_cvt_pk_bf16_f32 v199, v200, v201
	v_cvt_pk_bf16_f32 v200, v202, v205
	s_waitcnt lgkmcnt(2)
	v_mfma_f32_32x32x16_bf16 v[64:79], v[242:245], v[118:121], v[64:79]
	ds_read_b128 v[242:245], v181 offset:32896
	v_cvt_pk_bf16_f32 v205, v215, v218
	v_permlane32_swap_b32_e32 v198, v200
	s_waitcnt lgkmcnt(2)
	v_mfma_f32_32x32x16_bf16 v[80:95], v[210:213], v[114:117], v[80:95]
	ds_read_b128 v[210:213], v181 offset:41088
	s_waitcnt lgkmcnt(2)
	v_mfma_f32_32x32x16_bf16 v[64:79], v[206:209], v[114:117], v[64:79]
	ds_read_b128 v[206:209], v182 offset:32896
	s_waitcnt lgkmcnt(2)
	v_mfma_f32_32x32x16_bf16 v[80:95], v[242:245], v[110:113], v[80:95]
	ds_read_b128 v[242:245], v182 offset:41088
	s_waitcnt lgkmcnt(2)
	v_mfma_f32_32x32x16_bf16 v[64:79], v[210:213], v[110:113], v[64:79]
	ds_read_b128 v[210:213], v180 offset:32896
	s_waitcnt lgkmcnt(2)
	v_mfma_f32_32x32x16_bf16 v[80:95], v[206:209], v[106:109], v[80:95]
	ds_read_b128 v[206:209], v180 offset:41088
	s_waitcnt lgkmcnt(2)
	v_mfma_f32_32x32x16_bf16 v[64:79], v[242:245], v[106:109], v[64:79]
	ds_read_b128 v[242:245], v151 offset:32896
	s_waitcnt lgkmcnt(2)
	v_mfma_f32_32x32x16_bf16 v[80:95], v[210:213], v[102:105], v[80:95]
	ds_read_b128 v[210:213], v151 offset:41088
	s_waitcnt lgkmcnt(2)
	v_mfma_f32_32x32x16_bf16 v[64:79], v[206:209], v[102:105], v[64:79]
	s_waitcnt lgkmcnt(1)
	v_mfma_f32_32x32x16_bf16 v[80:95], v[242:245], v[98:101], v[80:95]
	v_exp_f32_e32 v208, v149
	v_exp_f32_e32 v209, v194
	v_cvt_pk_bf16_f32 v149, v138, v140
	v_cvt_pk_bf16_f32 v194, v133, v135
	v_add_f32_e32 v146, v208, v146
	v_add_f32_e32 v146, v193, v146
	v_add_f32_e32 v146, v209, v146
	s_waitcnt lgkmcnt(0)
	v_mfma_f32_32x32x16_bf16 v[64:79], v[210:213], v[98:101], v[64:79]
	v_exp_f32_e32 v210, v195
	v_exp_f32_e32 v211, v196
	v_exp_f32_e32 v212, v197
	v_exp_f32_e32 v213, v147
	v_add_f32_e32 v146, v210, v146
	v_add_f32_e32 v146, v211, v146
	v_add_f32_e32 v146, v212, v146
	v_add_f32_e32 v146, v213, v146
	v_add_f32_e32 v146, v214, v146
	v_add_f32_e32 v146, v215, v146
	v_add_f32_e32 v206, v218, v146
	v_mov_b32_e32 v207, v206
	s_nop 1
	v_permlane32_swap_b32_e32 v206, v207
	v_cvt_pk_bf16_f32 v146, v139, v141
	v_cvt_pk_bf16_f32 v147, v142, v143
	v_cvt_pk_bf16_f32 v195, v136, v137
	v_cvt_pk_bf16_f32 v196, v130, v131
	v_cvt_pk_bf16_f32 v197, v132, v134
	v_cvt_pk_bf16_f32 v201, v208, v193
	v_cvt_pk_bf16_f32 v202, v209, v210
	v_cvt_pk_bf16_f32 v203, v211, v212
	v_cvt_pk_bf16_f32 v204, v213, v214
	v_permlane32_swap_b32_e32 v146, v148
	v_permlane32_swap_b32_e32 v147, v149
	v_permlane32_swap_b32_e32 v194, v196
	v_permlane32_swap_b32_e32 v195, v197
	v_permlane32_swap_b32_e32 v199, v201
	v_permlane32_swap_b32_e32 v202, v204
	v_permlane32_swap_b32_e32 v203, v205
	v_lshl_add_u64 v[130:131], v[164:165], 0, v[96:97]
	v_lshl_add_u64 v[134:135], v[160:161], 0, v[96:97]
	v_lshl_add_u64 v[138:139], v[166:167], 0, v[96:97]
	v_lshl_add_u64 v[142:143], v[162:163], 0, v[96:97]
	global_load_dwordx4 v[130:133], v[130:131], off
	s_nop 0
	global_load_dwordx4 v[134:137], v[134:135], off
	s_nop 0
	global_load_dwordx4 v[138:141], v[138:139], off
	s_nop 0
	global_load_dwordx4 v[142:145], v[142:143], off
	s_cmp_le_i32 s92, s41
	s_cbranch_scc0 .Lpvm_1167b
	ds_read_b64_tr_b16 v[208:209], v174 offset:0x4000
	ds_read_b64_tr_b16 v[210:211], v174 offset:0x4800
	ds_read_b64_tr_b16 v[220:221], v174 offset:0x5000
	ds_read_b64_tr_b16 v[222:223], v174 offset:0x5800
	ds_read_b64_tr_b16 v[224:225], v174 offset:0x6000
	ds_read_b64_tr_b16 v[226:227], v174 offset:0x6800
	ds_read_b64_tr_b16 v[238:239], v174 offset:0x7000
	ds_read_b64_tr_b16 v[240:241], v174 offset:0x7800
	s_nop 0
	s_waitcnt lgkmcnt(6)
	v_mfma_f32_32x32x16_bf16 v[48:63], v[146:149], v[208:211], v[48:63]
	v_max_f32_e32 v230, v81, v81
	v_max_f32_e32 v231, v80, v80
	v_max_f32_e32 v230, v231, v230
	ds_read_b64_tr_b16 v[208:209], v174 offset:0x4200
	ds_read_b64_tr_b16 v[210:211], v174 offset:0x4a00
	s_waitcnt lgkmcnt(6)
	v_mfma_f32_32x32x16_bf16 v[48:63], v[194:197], v[220:223], v[48:63]
	v_max3_f32 v230, v230, v82, v83
	v_max3_f32 v230, v230, v84, v85
	v_max3_f32 v230, v230, v86, v87
	ds_read_b64_tr_b16 v[220:221], v174 offset:0x5200
	ds_read_b64_tr_b16 v[222:223], v174 offset:0x5a00
	s_waitcnt lgkmcnt(6)
	v_mfma_f32_32x32x16_bf16 v[48:63], v[198:201], v[224:227], v[48:63]
	v_max3_f32 v230, v230, v88, v89
	v_max3_f32 v230, v230, v90, v91
	v_max3_f32 v230, v230, v92, v93
	ds_read_b64_tr_b16 v[224:225], v174 offset:0x6200
	ds_read_b64_tr_b16 v[226:227], v174 offset:0x6a00
	s_waitcnt lgkmcnt(6)
	v_mfma_f32_32x32x16_bf16 v[48:63], v[202:205], v[238:241], v[48:63]
	v_max3_f32 v230, v230, v94, v95
	v_max3_f32 v230, v230, v64, v65
	v_max3_f32 v230, v230, v66, v67
	ds_read_b64_tr_b16 v[238:239], v174 offset:0x7200
	ds_read_b64_tr_b16 v[240:241], v174 offset:0x7a00
	s_waitcnt lgkmcnt(6)
	v_mfma_f32_32x32x16_bf16 v[32:47], v[146:149], v[208:211], v[32:47]
	v_max3_f32 v230, v230, v68, v69
	v_max3_f32 v230, v230, v70, v71
	v_max3_f32 v230, v230, v72, v73
	ds_read_b64_tr_b16 v[208:209], v174 offset:0x4400
	ds_read_b64_tr_b16 v[210:211], v174 offset:0x4c00
	s_waitcnt lgkmcnt(6)
	v_mfma_f32_32x32x16_bf16 v[32:47], v[194:197], v[220:223], v[32:47]
	v_max3_f32 v230, v230, v74, v75
	v_max3_f32 v230, v230, v76, v77
	v_max3_f32 v230, v230, v78, v79
	ds_read_b64_tr_b16 v[220:221], v174 offset:0x5400
	ds_read_b64_tr_b16 v[222:223], v174 offset:0x5c00
	s_waitcnt lgkmcnt(6)
	v_mfma_f32_32x32x16_bf16 v[32:47], v[198:201], v[224:227], v[32:47]
	v_mov_b32_e32 v231, v230
	s_nop 1
	v_permlane32_swap_b32_e32 v230, v231
	ds_read_b64_tr_b16 v[224:225], v174 offset:0x6400
	ds_read_b64_tr_b16 v[226:227], v174 offset:0x6c00
	s_waitcnt lgkmcnt(6)
	v_mfma_f32_32x32x16_bf16 v[32:47], v[202:205], v[238:241], v[32:47]
	v_max_f32_e32 v231, v231, v231
	v_max_f32_e32 v230, v230, v230
	v_max_f32_e32 v230, v230, v231
	ds_read_b64_tr_b16 v[238:239], v174 offset:0x7400
	ds_read_b64_tr_b16 v[240:241], v174 offset:0x7c00
	s_waitcnt lgkmcnt(6)
	v_mfma_f32_32x32x16_bf16 v[16:31], v[146:149], v[208:211], v[16:31]
	v_sub_f32_e32 v231, v230, v187
	v_mul_f32_e32 v231, 0x3db504f3, v231
	s_mov_b32 s6, 0x41000000
	ds_read_b64_tr_b16 v[208:209], v174 offset:0x4600
	ds_read_b64_tr_b16 v[210:211], v174 offset:0x4e00
	s_waitcnt lgkmcnt(6)
	v_mfma_f32_32x32x16_bf16 v[16:31], v[194:197], v[220:223], v[16:31]
	v_cmp_ge_f32_e32 vcc, s6, v231
	v_max_f32_e32 v231, v187, v187
	v_max_f32_e32 v231, v231, v230
	ds_read_b64_tr_b16 v[220:221], v174 offset:0x5600
	ds_read_b64_tr_b16 v[222:223], v174 offset:0x5e00
	s_waitcnt lgkmcnt(6)
	v_mfma_f32_32x32x16_bf16 v[16:31], v[198:201], v[224:227], v[16:31]
	v_sub_f32_e32 v230, v187, v231
	v_mul_f32_e32 v230, 0x3e0293ee, v230
	v_exp_f32_e32 v230, v230
	ds_read_b64_tr_b16 v[224:225], v174 offset:0x6600
	ds_read_b64_tr_b16 v[226:227], v174 offset:0x6e00
	s_waitcnt lgkmcnt(6)
	v_mfma_f32_32x32x16_bf16 v[16:31], v[202:205], v[238:241], v[16:31]
	ds_read_b64_tr_b16 v[238:239], v174 offset:0x7600
	ds_read_b64_tr_b16 v[240:241], v174 offset:0x7e00
	s_waitcnt lgkmcnt(6)
	v_mfma_f32_32x32x16_bf16 v[0:15], v[146:149], v[208:211], v[0:15]
	s_waitcnt lgkmcnt(4)
	v_mfma_f32_32x32x16_bf16 v[0:15], v[194:197], v[220:223], v[0:15]
	s_waitcnt lgkmcnt(2)
	v_mfma_f32_32x32x16_bf16 v[0:15], v[198:201], v[224:227], v[0:15]
	s_waitcnt lgkmcnt(0)
	v_mfma_f32_32x32x16_bf16 v[0:15], v[202:205], v[238:241], v[0:15]
	s_nop 0
	v_mov_b32_e32 v146, v230
	v_mov_b32_e32 v147, v231
	s_branch .Lpvj_1167b

.LBB0_1354:
	ds_read_b128 v[80:83], v193
	ds_read_b128 v[84:87], v193 offset:32
	ds_read_b128 v[64:67], v193 offset:128
	ds_read_b128 v[68:71], v193 offset:160
	ds_read_b128 v[88:91], v193 offset:64
	ds_read_b128 v[72:75], v193 offset:192
	ds_read_b128 v[92:95], v193 offset:96
	ds_read_b128 v[76:79], v193 offset:224
	s_waitcnt vmcnt(2)
	ds_read_b128 v[134:137], v187 offset:49152
	ds_read_b128 v[130:133], v187 offset:57344
	ds_read_b128 v[242:245], v188 offset:49152
	s_waitcnt vmcnt(2)
	s_waitcnt vmcnt(1)
	v_exp_f32_e32 v138, v146
	v_add_f32_e32 v146, 0, v203
	v_add_f32_e32 v146, v204, v146
	s_waitcnt lgkmcnt(2)
	v_mfma_f32_32x32x16_bf16 v[80:95], v[134:137], v[126:129], v[80:95]
	ds_read_b128 v[134:137], v188 offset:57344
	v_add_f32_e32 v146, v205, v146
	v_add_f32_e32 v146, v207, v146
	v_add_f32_e32 v146, v208, v146
	v_add_f32_e32 v146, v210, v146
	v_add_f32_e32 v146, v206, v146
	v_add_f32_e32 v146, v209, v146
	v_add_f32_e32 v146, v173, v146
	s_waitcnt lgkmcnt(2)
	v_mfma_f32_32x32x16_bf16 v[64:79], v[130:133], v[126:129], v[64:79]
	ds_read_b128 v[130:133], v186 offset:49152
	v_add_f32_e32 v146, v175, v146
	v_add_f32_e32 v146, v198, v146
	v_add_f32_e32 v146, v201, v146
	v_add_f32_e32 v146, v174, v146
	v_add_f32_e32 v146, v199, v146
	v_add_f32_e32 v146, v200, v146
	s_waitcnt lgkmcnt(2)
	v_mfma_f32_32x32x16_bf16 v[80:95], v[242:245], v[122:125], v[80:95]
	ds_read_b128 v[242:245], v186 offset:57344
	v_add_f32_e32 v146, v202, v146
	v_exp_f32_e32 v139, v147
	v_exp_f32_e32 v140, v160
	v_exp_f32_e32 v141, v161
	s_waitcnt vmcnt(0)
	v_exp_f32_e32 v142, v154
	v_exp_f32_e32 v143, v155
	v_exp_f32_e32 v144, v148
	s_waitcnt lgkmcnt(2)
	v_mfma_f32_32x32x16_bf16 v[64:79], v[134:137], v[122:125], v[64:79]
	ds_read_b128 v[134:137], v167 offset:49152
	v_exp_f32_e32 v145, v149
	v_cvt_pk_bf16_f32 v147, v205, v207
	v_cvt_pk_bf16_f32 v148, v208, v210
	v_cvt_pk_bf16_f32 v149, v206, v209
	v_cvt_pk_bf16_f32 v160, v142, v143
	v_cvt_pk_bf16_f32 v161, v144, v145
	s_waitcnt lgkmcnt(2)
	v_mfma_f32_32x32x16_bf16 v[80:95], v[130:133], v[118:121], v[80:95]
	ds_read_b128 v[130:133], v167 offset:57344
	v_permlane32_swap_b32_e32 v147, v149
	s_waitcnt lgkmcnt(2)
	v_mfma_f32_32x32x16_bf16 v[64:79], v[242:245], v[118:121], v[64:79]
	ds_read_b128 v[242:245], v187 offset:49280
	s_waitcnt lgkmcnt(2)
	v_mfma_f32_32x32x16_bf16 v[80:95], v[134:137], v[114:117], v[80:95]
	ds_read_b128 v[134:137], v187 offset:57472
	s_waitcnt lgkmcnt(2)
	v_mfma_f32_32x32x16_bf16 v[64:79], v[130:133], v[114:117], v[64:79]
	ds_read_b128 v[130:133], v188 offset:49280
	s_waitcnt lgkmcnt(2)
	v_mfma_f32_32x32x16_bf16 v[80:95], v[242:245], v[110:113], v[80:95]
	ds_read_b128 v[242:245], v188 offset:57472
	s_waitcnt lgkmcnt(2)
	v_mfma_f32_32x32x16_bf16 v[64:79], v[134:137], v[110:113], v[64:79]
	ds_read_b128 v[134:137], v186 offset:49280
	s_waitcnt lgkmcnt(2)
	v_mfma_f32_32x32x16_bf16 v[80:95], v[130:133], v[106:109], v[80:95]
	ds_read_b128 v[130:133], v186 offset:57472
	s_waitcnt lgkmcnt(2)
	v_mfma_f32_32x32x16_bf16 v[64:79], v[242:245], v[106:109], v[64:79]
	ds_read_b128 v[242:245], v167 offset:49280
	s_waitcnt lgkmcnt(2)
	v_mfma_f32_32x32x16_bf16 v[80:95], v[134:137], v[102:105], v[80:95]
	ds_read_b128 v[134:137], v167 offset:57472
	s_waitcnt lgkmcnt(2)
	v_mfma_f32_32x32x16_bf16 v[64:79], v[130:133], v[102:105], v[64:79]
	s_waitcnt lgkmcnt(1)
	v_mfma_f32_32x32x16_bf16 v[80:95], v[242:245], v[98:101], v[80:95]
	v_exp_f32_e32 v130, v158
	v_exp_f32_e32 v131, v159
	v_exp_f32_e32 v132, v156
	v_exp_f32_e32 v133, v157
	v_add_f32_e32 v146, v130, v146
	v_add_f32_e32 v146, v131, v146
	v_add_f32_e32 v146, v132, v146
	s_waitcnt lgkmcnt(0)
	v_mfma_f32_32x32x16_bf16 v[64:79], v[134:137], v[98:101], v[64:79]
	v_exp_f32_e32 v134, v152
	v_exp_f32_e32 v135, v153
	v_exp_f32_e32 v136, v150
	v_exp_f32_e32 v137, v151
	v_add_f32_e32 v146, v133, v146
	v_add_f32_e32 v146, v134, v146
	v_add_f32_e32 v146, v135, v146
	v_add_f32_e32 v146, v136, v146
	v_add_f32_e32 v146, v137, v146
	v_add_f32_e32 v146, v138, v146
	v_add_f32_e32 v146, v139, v146
	v_add_f32_e32 v146, v140, v146
	v_add_f32_e32 v146, v141, v146
	v_add_f32_e32 v146, v142, v146
	v_add_f32_e32 v146, v143, v146
	v_add_f32_e32 v146, v144, v146
	v_add_f32_e32 v195, v145, v146
	v_mov_b32_e32 v196, v195
	s_nop 1
	v_permlane32_swap_b32_e32 v195, v196
	v_cvt_pk_bf16_f32 v146, v203, v204
	v_cvt_pk_bf16_f32 v150, v173, v175
	v_cvt_pk_bf16_f32 v151, v198, v201
	v_cvt_pk_bf16_f32 v152, v174, v199
	v_cvt_pk_bf16_f32 v153, v200, v202
	v_cvt_pk_bf16_f32 v154, v130, v131
	v_cvt_pk_bf16_f32 v155, v132, v133
	v_cvt_pk_bf16_f32 v156, v134, v135
	v_cvt_pk_bf16_f32 v157, v136, v137
	v_cvt_pk_bf16_f32 v158, v138, v139
	v_cvt_pk_bf16_f32 v159, v140, v141
	v_permlane32_swap_b32_e32 v146, v148
	v_permlane32_swap_b32_e32 v150, v152
	v_permlane32_swap_b32_e32 v151, v153
	v_permlane32_swap_b32_e32 v154, v156
	v_permlane32_swap_b32_e32 v155, v157
	v_permlane32_swap_b32_e32 v158, v160
	v_permlane32_swap_b32_e32 v159, v161
	v_lshl_add_u64 v[174:175], v[168:169], 0, v[96:97]
	s_mov_b32 s6, 0x15c40000
	v_add_co_u32_e32 v130, vcc, s6, v174
	s_mov_b32 s6, 0x15c50000
	s_nop 0
	v_addc_co_u32_e32 v131, vcc, 0, v175, vcc
	v_add_co_u32_e32 v134, vcc, s6, v174
	v_lshl_add_u64 v[172:173], v[170:171], 0, v[96:97]
	s_nop 0
	v_addc_co_u32_e32 v135, vcc, 0, v175, vcc
	s_mov_b32 s6, 0x14b40000
	v_add_co_u32_e32 v138, vcc, s6, v172
	s_mov_b32 s6, 0x14b50000
	s_nop 0
	v_addc_co_u32_e32 v139, vcc, 0, v173, vcc
	v_add_co_u32_e32 v142, vcc, s6, v172
	global_load_dwordx4 v[130:133], v[130:131], off
	s_nop 0
	global_load_dwordx4 v[134:137], v[134:135], off
	v_addc_co_u32_e32 v143, vcc, 0, v173, vcc
	global_load_dwordx4 v[138:141], v[138:139], off
	s_nop 0
	global_load_dwordx4 v[142:145], v[142:143], off
	s_sub_i32 s6, s92, 64
	s_cmp_le_i32 s6, s41
	s_cbranch_scc0 .Lpvm_1354a
	ds_read_b64_tr_b16 v[198:199], v180 offset:0
	ds_read_b64_tr_b16 v[200:201], v180 offset:0x800
	ds_read_b64_tr_b16 v[202:203], v180 offset:0x1000
	ds_read_b64_tr_b16 v[204:205], v180 offset:0x1800
	ds_read_b64_tr_b16 v[206:207], v180 offset:0x2000
	ds_read_b64_tr_b16 v[208:209], v180 offset:0x2800
	ds_read_b64_tr_b16 v[210:211], v180 offset:0x3000
	ds_read_b64_tr_b16 v[212:213], v180 offset:0x3800
	s_nop 0
	s_waitcnt lgkmcnt(6)
	v_mfma_f32_32x32x16_bf16 v[48:63], v[146:149], v[198:201], v[48:63]
	v_max_f32_e32 v230, v81, v81
	v_max_f32_e32 v231, v80, v80
	v_max_f32_e32 v230, v231, v230
	ds_read_b64_tr_b16 v[198:199], v180 offset:0x200
	ds_read_b64_tr_b16 v[200:201], v180 offset:0xa00
	s_waitcnt lgkmcnt(6)
	v_mfma_f32_32x32x16_bf16 v[48:63], v[150:153], v[202:205], v[48:63]
	v_max3_f32 v230, v230, v82, v83
	v_max3_f32 v230, v230, v84, v85
	v_max3_f32 v230, v230, v86, v87
	ds_read_b64_tr_b16 v[202:203], v180 offset:0x1200
	ds_read_b64_tr_b16 v[204:205], v180 offset:0x1a00
	s_waitcnt lgkmcnt(6)
	v_mfma_f32_32x32x16_bf16 v[48:63], v[154:157], v[206:209], v[48:63]
	v_max3_f32 v230, v230, v88, v89
	v_max3_f32 v230, v230, v90, v91
	v_max3_f32 v230, v230, v92, v93
	ds_read_b64_tr_b16 v[206:207], v180 offset:0x2200
	ds_read_b64_tr_b16 v[208:209], v180 offset:0x2a00
	s_waitcnt lgkmcnt(6)
	v_mfma_f32_32x32x16_bf16 v[48:63], v[158:161], v[210:213], v[48:63]
	v_max3_f32 v230, v230, v94, v95
	v_max3_f32 v230, v230, v64, v65
	v_max3_f32 v230, v230, v66, v67
	ds_read_b64_tr_b16 v[210:211], v180 offset:0x3200
	ds_read_b64_tr_b16 v[212:213], v180 offset:0x3a00
	s_waitcnt lgkmcnt(6)
	v_mfma_f32_32x32x16_bf16 v[32:47], v[146:149], v[198:201], v[32:47]
	v_max3_f32 v230, v230, v68, v69
	v_max3_f32 v230, v230, v70, v71
	v_max3_f32 v230, v230, v72, v73
	ds_read_b64_tr_b16 v[198:199], v180 offset:0x400
	ds_read_b64_tr_b16 v[200:201], v180 offset:0xc00
	s_waitcnt lgkmcnt(6)
	v_mfma_f32_32x32x16_bf16 v[32:47], v[150:153], v[202:205], v[32:47]
	v_max3_f32 v230, v230, v74, v75
	v_max3_f32 v230, v230, v76, v77
	v_max3_f32 v230, v230, v78, v79
	ds_read_b64_tr_b16 v[202:203], v180 offset:0x1400
	ds_read_b64_tr_b16 v[204:205], v180 offset:0x1c00
	s_waitcnt lgkmcnt(6)
	v_mfma_f32_32x32x16_bf16 v[32:47], v[154:157], v[206:209], v[32:47]
	v_mov_b32_e32 v231, v230
	s_nop 1
	v_permlane32_swap_b32_e32 v230, v231
	ds_read_b64_tr_b16 v[206:207], v180 offset:0x2400
	ds_read_b64_tr_b16 v[208:209], v180 offset:0x2c00
	s_waitcnt lgkmcnt(6)
	v_mfma_f32_32x32x16_bf16 v[32:47], v[158:161], v[210:213], v[32:47]
	v_max_f32_e32 v231, v231, v231
	v_max_f32_e32 v230, v230, v230
	v_max_f32_e32 v230, v230, v231
	ds_read_b64_tr_b16 v[210:211], v180 offset:0x3400
	ds_read_b64_tr_b16 v[212:213], v180 offset:0x3c00
	s_waitcnt lgkmcnt(6)
	v_mfma_f32_32x32x16_bf16 v[16:31], v[146:149], v[198:201], v[16:31]
	v_sub_f32_e32 v231, v230, v194
	v_mul_f32_e32 v231, 0x3db504f3, v231
	s_mov_b32 s6, 0x41000000
	ds_read_b64_tr_b16 v[198:199], v180 offset:0x600
	ds_read_b64_tr_b16 v[200:201], v180 offset:0xe00
	s_waitcnt lgkmcnt(6)
	v_mfma_f32_32x32x16_bf16 v[16:31], v[150:153], v[202:205], v[16:31]
	v_cmp_ge_f32_e32 vcc, s6, v231
	v_max_f32_e32 v231, v194, v194
	v_max_f32_e32 v230, v231, v230
	ds_read_b64_tr_b16 v[202:203], v180 offset:0x1600
	ds_read_b64_tr_b16 v[204:205], v180 offset:0x1e00
	s_waitcnt lgkmcnt(6)
	v_mfma_f32_32x32x16_bf16 v[16:31], v[154:157], v[206:209], v[16:31]
	v_sub_f32_e32 v231, v194, v230
	v_mul_f32_e32 v231, 0x3e0293ee, v231
	v_exp_f32_e32 v231, v231
	ds_read_b64_tr_b16 v[206:207], v180 offset:0x2600
	ds_read_b64_tr_b16 v[208:209], v180 offset:0x2e00
	s_waitcnt lgkmcnt(6)
	v_mfma_f32_32x32x16_bf16 v[16:31], v[158:161], v[210:213], v[16:31]
	ds_read_b64_tr_b16 v[210:211], v180 offset:0x3600
	ds_read_b64_tr_b16 v[212:213], v180 offset:0x3e00
	s_waitcnt lgkmcnt(6)
	v_mfma_f32_32x32x16_bf16 v[0:15], v[146:149], v[198:201], v[0:15]
	s_waitcnt lgkmcnt(4)
	v_mfma_f32_32x32x16_bf16 v[0:15], v[150:153], v[202:205], v[0:15]
	s_waitcnt lgkmcnt(2)
	v_mfma_f32_32x32x16_bf16 v[0:15], v[154:157], v[206:209], v[0:15]
	s_waitcnt lgkmcnt(0)
	v_mfma_f32_32x32x16_bf16 v[0:15], v[158:161], v[210:213], v[0:15]
	s_nop 0
	v_mov_b32_e32 v146, v230
	v_mov_b32_e32 v147, v231
	s_branch .Lpvj_1354a

.LBB0_1360:
	v_cndmask_b32_e64 v194, v146, v194, s[6:7]
	v_mul_f32_e32 v198, 0xbe0293ee, v194
	v_fmamk_f32 v80, v80, 0x3e0293ee, v198
	v_fmamk_f32 v81, v81, 0x3e0293ee, v198
	v_fmamk_f32 v82, v82, 0x3e0293ee, v198
	v_fmamk_f32 v83, v83, 0x3e0293ee, v198
	v_fmamk_f32 v84, v84, 0x3e0293ee, v198
	v_fmamk_f32 v85, v85, 0x3e0293ee, v198
	v_fmamk_f32 v86, v86, 0x3e0293ee, v198
	v_fmamk_f32 v87, v87, 0x3e0293ee, v198
	v_fmamk_f32 v88, v88, 0x3e0293ee, v198
	v_fmamk_f32 v89, v89, 0x3e0293ee, v198
	v_fmamk_f32 v90, v90, 0x3e0293ee, v198
	v_fmamk_f32 v91, v91, 0x3e0293ee, v198
	v_fmamk_f32 v92, v92, 0x3e0293ee, v198
	v_fmamk_f32 v93, v93, 0x3e0293ee, v198
	v_fmamk_f32 v94, v94, 0x3e0293ee, v198
	v_fmamk_f32 v95, v95, 0x3e0293ee, v198
	v_exp_f32_e32 v146, v80
	v_exp_f32_e32 v147, v81
	v_exp_f32_e32 v148, v82
	v_exp_f32_e32 v159, v83
	v_exp_f32_e32 v160, v84
	v_exp_f32_e32 v161, v85
	v_exp_f32_e32 v149, v86
	v_exp_f32_e32 v158, v87
	v_exp_f32_e32 v150, v88
	v_exp_f32_e32 v151, v89
	v_exp_f32_e32 v156, v90
	v_exp_f32_e32 v157, v91
	v_exp_f32_e32 v152, v92
	v_exp_f32_e32 v153, v93
	v_exp_f32_e32 v154, v94
	v_exp_f32_e32 v155, v95
	v_fmamk_f32 v211, v68, 0x3e0293ee, v198
	v_fmamk_f32 v212, v77, 0x3e0293ee, v198
	v_fmamk_f32 v207, v64, 0x3e0293ee, v198
	v_fmamk_f32 v208, v65, 0x3e0293ee, v198
	v_fmamk_f32 v209, v66, 0x3e0293ee, v198
	v_fmamk_f32 v210, v67, 0x3e0293ee, v198
	v_fmamk_f32 v200, v69, 0x3e0293ee, v198
	v_fmamk_f32 v201, v70, 0x3e0293ee, v198
	v_fmamk_f32 v202, v71, 0x3e0293ee, v198
	v_fmamk_f32 v203, v72, 0x3e0293ee, v198
	v_fmamk_f32 v204, v73, 0x3e0293ee, v198
	v_fmamk_f32 v205, v74, 0x3e0293ee, v198
	v_fmamk_f32 v206, v75, 0x3e0293ee, v198
	v_fmamk_f32 v199, v76, 0x3e0293ee, v198
	v_fmamk_f32 v213, v78, 0x3e0293ee, v198
	v_fmac_f32_e32 v198, 0x3e0293ee, v79
	s_waitcnt lgkmcnt(0)
	s_barrier
	ds_read_b128 v[80:83], v193 offset:256
	ds_read_b128 v[84:87], v193 offset:288
	ds_read_b128 v[64:67], v193 offset:384
	ds_read_b128 v[68:71], v193 offset:416
	ds_read_b128 v[88:91], v193 offset:320
	ds_read_b128 v[72:75], v193 offset:448
	ds_read_b128 v[92:95], v193 offset:352
	ds_read_b128 v[76:79], v193 offset:480
	ds_read_b128 v[224:227], v187 offset:32768
	ds_read_b128 v[220:223], v187 offset:40960
	ds_read_b128 v[242:245], v188 offset:32768
	v_exp_f32_e32 v214, v211
	v_add_f32_e32 v211, 0, v146
	v_add_f32_e32 v211, v147, v211
	s_waitcnt lgkmcnt(2)
	v_mfma_f32_32x32x16_bf16 v[80:95], v[224:227], v[126:129], v[80:95]
	ds_read_b128 v[224:227], v188 offset:40960
	v_add_f32_e32 v211, v148, v211
	v_add_f32_e32 v211, v159, v211
	v_add_f32_e32 v211, v160, v211
	v_add_f32_e32 v211, v161, v211
	v_add_f32_e32 v211, v149, v211
	v_add_f32_e32 v211, v158, v211
	v_add_f32_e32 v211, v150, v211
	s_waitcnt lgkmcnt(2)
	v_mfma_f32_32x32x16_bf16 v[64:79], v[220:223], v[126:129], v[64:79]
	ds_read_b128 v[220:223], v186 offset:32768
	v_add_f32_e32 v211, v151, v211
	v_add_f32_e32 v211, v156, v211
	v_add_f32_e32 v211, v157, v211
	v_exp_f32_e32 v207, v207
	v_add_f32_e32 v211, v152, v211
	v_exp_f32_e32 v208, v208
	s_waitcnt lgkmcnt(2)
	v_mfma_f32_32x32x16_bf16 v[80:95], v[242:245], v[122:125], v[80:95]
	ds_read_b128 v[242:245], v186 offset:40960
	v_add_f32_e32 v211, v153, v211
	v_exp_f32_e32 v209, v209
	v_add_f32_e32 v211, v154, v211
	v_exp_f32_e32 v210, v210
	v_add_f32_e32 v211, v155, v211
	v_add_f32_e32 v211, v207, v211
	v_exp_f32_e32 v200, v200
	s_waitcnt lgkmcnt(2)
	v_mfma_f32_32x32x16_bf16 v[64:79], v[224:227], v[122:125], v[64:79]
	ds_read_b128 v[224:227], v167 offset:32768
	v_add_f32_e32 v211, v208, v211
	v_exp_f32_e32 v201, v201
	v_add_f32_e32 v211, v209, v211
	v_exp_f32_e32 v202, v202
	v_add_f32_e32 v211, v210, v211
	v_exp_f32_e32 v203, v203
	s_waitcnt lgkmcnt(2)
	v_mfma_f32_32x32x16_bf16 v[80:95], v[220:223], v[118:121], v[80:95]
	ds_read_b128 v[220:223], v167 offset:40960
	v_add_f32_e32 v211, v214, v211
	v_exp_f32_e32 v204, v204
	v_add_f32_e32 v211, v200, v211
	v_exp_f32_e32 v205, v205
	v_add_f32_e32 v211, v201, v211
	v_exp_f32_e32 v206, v206
	v_add_f32_e32 v211, v202, v211
	s_waitcnt lgkmcnt(2)
	v_mfma_f32_32x32x16_bf16 v[64:79], v[242:245], v[118:121], v[64:79]
	ds_read_b128 v[242:245], v187 offset:32896
	v_exp_f32_e32 v199, v199
	v_add_f32_e32 v211, v203, v211
	v_exp_f32_e32 v215, v212
	v_add_f32_e32 v211, v204, v211
	v_exp_f32_e32 v213, v213
	v_add_f32_e32 v211, v205, v211
	s_waitcnt lgkmcnt(2)
	v_mfma_f32_32x32x16_bf16 v[80:95], v[224:227], v[114:117], v[80:95]
	ds_read_b128 v[224:227], v187 offset:41088
	v_exp_f32_e32 v198, v198
	v_add_f32_e32 v211, v206, v211
	v_add_f32_e32 v211, v199, v211
	v_add_f32_e32 v211, v215, v211
	v_add_f32_e32 v211, v213, v211
	v_add_f32_e32 v211, v198, v211
	v_mov_b32_e32 v212, v211
	s_waitcnt lgkmcnt(2)
	v_mfma_f32_32x32x16_bf16 v[64:79], v[220:223], v[114:117], v[64:79]
	ds_read_b128 v[220:223], v188 offset:32896
	v_cvt_pk_bf16_f32 v146, v146, v147
	v_cvt_pk_bf16_f32 v147, v148, v159
	v_cvt_pk_bf16_f32 v148, v160, v161
	v_cvt_pk_bf16_f32 v149, v149, v158
	v_cvt_pk_bf16_f32 v150, v150, v151
	v_cvt_pk_bf16_f32 v151, v156, v157
	s_waitcnt lgkmcnt(2)
	v_mfma_f32_32x32x16_bf16 v[80:95], v[242:245], v[110:113], v[80:95]
	ds_read_b128 v[242:245], v188 offset:41088
	v_cvt_pk_bf16_f32 v152, v152, v153
	v_cvt_pk_bf16_f32 v153, v154, v155
	v_cvt_pk_bf16_f32 v154, v207, v208
	v_cvt_pk_bf16_f32 v155, v209, v210
	v_cvt_pk_bf16_f32 v156, v214, v200
	v_cvt_pk_bf16_f32 v157, v201, v202
	v_cvt_pk_bf16_f32 v158, v203, v204
	s_waitcnt lgkmcnt(2)
	v_mfma_f32_32x32x16_bf16 v[64:79], v[224:227], v[110:113], v[64:79]
	ds_read_b128 v[224:227], v186 offset:32896
	v_cvt_pk_bf16_f32 v159, v205, v206
	v_cvt_pk_bf16_f32 v160, v199, v215
	v_cvt_pk_bf16_f32 v161, v213, v198
	v_permlane32_swap_b32_e32 v211, v212
	v_permlane32_swap_b32_e32 v146, v148
	s_waitcnt lgkmcnt(2)
	v_mfma_f32_32x32x16_bf16 v[80:95], v[220:223], v[106:109], v[80:95]
	ds_read_b128 v[220:223], v186 offset:41088
	v_permlane32_swap_b32_e32 v147, v149
	v_permlane32_swap_b32_e32 v150, v152
	v_permlane32_swap_b32_e32 v151, v153
	v_permlane32_swap_b32_e32 v154, v156
	s_waitcnt lgkmcnt(2)
	v_mfma_f32_32x32x16_bf16 v[64:79], v[242:245], v[106:109], v[64:79]
	ds_read_b128 v[242:245], v167 offset:32896
	v_permlane32_swap_b32_e32 v155, v157
	v_permlane32_swap_b32_e32 v158, v160
	v_permlane32_swap_b32_e32 v159, v161
	s_waitcnt lgkmcnt(2)
	v_mfma_f32_32x32x16_bf16 v[80:95], v[224:227], v[102:105], v[80:95]
	ds_read_b128 v[224:227], v167 offset:41088
	s_waitcnt lgkmcnt(2)
	v_mfma_f32_32x32x16_bf16 v[64:79], v[220:223], v[102:105], v[64:79]
	s_waitcnt lgkmcnt(1)
	v_mfma_f32_32x32x16_bf16 v[80:95], v[242:245], v[98:101], v[80:95]
	s_waitcnt lgkmcnt(0)
	v_mfma_f32_32x32x16_bf16 v[64:79], v[224:227], v[98:101], v[64:79]
	s_add_i32 s6, s81, 1
	s_cmp_lt_u32 s6, s71
	s_cselect_b64 s[96:97], -1, 0
	s_cmp_ge_u32 s6, s71
	s_cbranch_scc1 .LBB0_1362
	v_add_co_u32_e32 v130, vcc, 0x15c60000, v174
	s_nop 1
	v_addc_co_u32_e32 v131, vcc, 0, v175, vcc
	v_add_co_u32_e32 v134, vcc, 0x15c70000, v174
	s_nop 1
	v_addc_co_u32_e32 v135, vcc, 0, v175, vcc
	v_add_co_u32_e32 v138, vcc, 0x14b60000, v172
	global_load_dwordx4 v[130:133], v[130:131], off
	s_nop 0
	global_load_dwordx4 v[134:137], v[134:135], off
	v_addc_co_u32_e32 v139, vcc, 0, v173, vcc
	v_add_co_u32_e32 v142, vcc, 0x14b70000, v172
	s_nop 1
	v_addc_co_u32_e32 v143, vcc, 0, v173, vcc
	global_load_dwordx4 v[138:141], v[138:139], off
	s_nop 0
	global_load_dwordx4 v[142:145], v[142:143], off

.LBB0_1518:
	ds_read_b128 v[80:83], v200
	ds_read_b128 v[84:87], v200 offset:32
	ds_read_b128 v[64:67], v200 offset:128
	ds_read_b128 v[68:71], v200 offset:160
	ds_read_b128 v[88:91], v200 offset:64
	ds_read_b128 v[72:75], v200 offset:192
	ds_read_b128 v[92:95], v200 offset:96
	ds_read_b128 v[76:79], v200 offset:224
	ds_read_b128 v[220:223], v194 offset:49152
	ds_read_b128 v[208:211], v194 offset:57344
	ds_read_b128 v[242:245], v195 offset:49152
	v_add_f32_e32 v146, 0, v147
	v_add_f32_e32 v146, v148, v146
	v_add_f32_e32 v146, v149, v146
	s_waitcnt lgkmcnt(2)
	v_mfma_f32_32x32x16_bf16 v[80:95], v[220:223], v[126:129], v[80:95]
	ds_read_b128 v[220:223], v195 offset:57344
	v_add_f32_e32 v146, v160, v146
	v_add_f32_e32 v146, v161, v146
	v_add_f32_e32 v146, v207, v146
	v_add_f32_e32 v146, v159, v146
	v_add_f32_e32 v146, v206, v146
	v_add_f32_e32 v146, v151, v146
	v_add_f32_e32 v146, v153, v146
	s_waitcnt lgkmcnt(2)
	v_mfma_f32_32x32x16_bf16 v[64:79], v[208:211], v[126:129], v[64:79]
	ds_read_b128 v[208:211], v193 offset:49152
	v_add_f32_e32 v146, v154, v146
	v_add_f32_e32 v146, v155, v146
	v_exp_f32_e32 v144, v144
	v_add_f32_e32 v146, v152, v146
	v_exp_f32_e32 v145, v145
	v_add_f32_e32 v146, v156, v146
	s_waitcnt lgkmcnt(2)
	v_mfma_f32_32x32x16_bf16 v[80:95], v[242:245], v[122:125], v[80:95]
	ds_read_b128 v[242:245], v193 offset:57344
	v_exp_f32_e32 v142, v142
	v_add_f32_e32 v146, v157, v146
	v_exp_f32_e32 v143, v143
	v_add_f32_e32 v146, v158, v146
	v_exp_f32_e32 v140, v140
	v_add_f32_e32 v146, v144, v146
	v_exp_f32_e32 v141, v141
	s_waitcnt lgkmcnt(2)
	v_mfma_f32_32x32x16_bf16 v[64:79], v[220:223], v[122:125], v[64:79]
	ds_read_b128 v[220:223], v192 offset:49152
	v_add_f32_e32 v146, v145, v146
	v_exp_f32_e32 v138, v138
	v_add_f32_e32 v146, v142, v146
	v_exp_f32_e32 v139, v139
	v_add_f32_e32 v146, v143, v146
	v_exp_f32_e32 v136, v136
	s_waitcnt lgkmcnt(2)
	v_mfma_f32_32x32x16_bf16 v[80:95], v[208:211], v[118:121], v[80:95]
	ds_read_b128 v[208:211], v192 offset:57344
	v_add_f32_e32 v146, v140, v146
	v_exp_f32_e32 v137, v137
	v_add_f32_e32 v146, v141, v146
	v_exp_f32_e32 v134, v134
	v_add_f32_e32 v146, v138, v146
	v_exp_f32_e32 v135, v135
	v_add_f32_e32 v146, v139, v146
	s_waitcnt lgkmcnt(2)
	v_mfma_f32_32x32x16_bf16 v[64:79], v[242:245], v[118:121], v[64:79]
	ds_read_b128 v[242:245], v194 offset:49280
	v_exp_f32_e32 v132, v132
	v_add_f32_e32 v146, v136, v146
	v_exp_f32_e32 v133, v133
	v_add_f32_e32 v146, v137, v146
	v_exp_f32_e32 v130, v130
	v_add_f32_e32 v146, v134, v146
	s_waitcnt lgkmcnt(2)
	v_mfma_f32_32x32x16_bf16 v[80:95], v[220:223], v[114:117], v[80:95]
	ds_read_b128 v[220:223], v194 offset:57472
	v_exp_f32_e32 v131, v131
	v_add_f32_e32 v146, v135, v146
	v_add_f32_e32 v146, v132, v146
	v_add_f32_e32 v146, v133, v146
	v_add_f32_e32 v146, v130, v146
	v_add_f32_e32 v203, v131, v146
	v_mov_b32_e32 v204, v203
	s_waitcnt lgkmcnt(2)
	v_mfma_f32_32x32x16_bf16 v[64:79], v[208:211], v[114:117], v[64:79]
	ds_read_b128 v[208:211], v195 offset:49280
	v_permlane32_swap_b32_e32 v203, v204
	v_cvt_pk_bf16_f32 v146, v147, v148
	v_cvt_pk_bf16_f32 v147, v149, v160
	v_cvt_pk_bf16_f32 v148, v161, v207
	v_cvt_pk_bf16_f32 v149, v159, v206
	s_waitcnt lgkmcnt(2)
	v_mfma_f32_32x32x16_bf16 v[80:95], v[242:245], v[110:113], v[80:95]
	ds_read_b128 v[242:245], v195 offset:57472
	v_cvt_pk_bf16_f32 v206, v151, v153
	v_cvt_pk_bf16_f32 v207, v154, v155
	v_cvt_pk_bf16_f32 v153, v142, v143
	v_cvt_pk_bf16_f32 v154, v140, v141
	v_cvt_pk_bf16_f32 v155, v138, v139
	v_cvt_pk_bf16_f32 v159, v130, v131
	v_permlane32_swap_b32_e32 v146, v148
	s_waitcnt lgkmcnt(2)
	v_mfma_f32_32x32x16_bf16 v[64:79], v[220:223], v[110:113], v[64:79]
	ds_read_b128 v[220:223], v193 offset:49280
	v_permlane32_swap_b32_e32 v147, v149
	v_permlane32_swap_b32_e32 v153, v155
	s_waitcnt lgkmcnt(2)
	v_mfma_f32_32x32x16_bf16 v[80:95], v[208:211], v[106:109], v[80:95]
	ds_read_b128 v[208:211], v193 offset:57472
	s_waitcnt lgkmcnt(2)
	v_mfma_f32_32x32x16_bf16 v[64:79], v[242:245], v[106:109], v[64:79]
	ds_read_b128 v[242:245], v192 offset:49280
	s_waitcnt lgkmcnt(2)
	v_mfma_f32_32x32x16_bf16 v[80:95], v[220:223], v[102:105], v[80:95]
	ds_read_b128 v[220:223], v192 offset:57472
	s_waitcnt lgkmcnt(2)
	v_mfma_f32_32x32x16_bf16 v[64:79], v[208:211], v[102:105], v[64:79]
	s_waitcnt lgkmcnt(1)
	v_mfma_f32_32x32x16_bf16 v[80:95], v[242:245], v[98:101], v[80:95]
	v_cvt_pk_bf16_f32 v208, v152, v156
	v_cvt_pk_bf16_f32 v209, v157, v158
	v_cvt_pk_bf16_f32 v152, v144, v145
	v_cvt_pk_bf16_f32 v156, v136, v137
	v_cvt_pk_bf16_f32 v157, v134, v135
	v_cvt_pk_bf16_f32 v158, v132, v133
	v_permlane32_swap_b32_e32 v206, v208
	s_waitcnt lgkmcnt(0)
	v_mfma_f32_32x32x16_bf16 v[64:79], v[220:223], v[98:101], v[64:79]
	v_permlane32_swap_b32_e32 v207, v209
	v_permlane32_swap_b32_e32 v152, v154
	v_permlane32_swap_b32_e32 v156, v158
	v_permlane32_swap_b32_e32 v157, v159
	v_lshl_add_u64 v[130:131], v[170:171], 0, v[96:97]
	v_lshl_add_u64 v[134:135], v[166:167], 0, v[96:97]
	v_lshl_add_u64 v[138:139], v[172:173], 0, v[96:97]
	v_lshl_add_u64 v[142:143], v[168:169], 0, v[96:97]
	global_load_dwordx4 v[130:133], v[130:131], off
	s_nop 0
	global_load_dwordx4 v[134:137], v[134:135], off
	s_nop 0
	global_load_dwordx4 v[138:141], v[138:139], off
	s_nop 0
	global_load_dwordx4 v[142:145], v[142:143], off
	s_sub_i32 s6, s74, 64
	s_cmp_le_i32 s6, s3
	s_cbranch_scc0 .Lpvm_1518a
	ds_read_b64_tr_b16 v[210:211], v188 offset:0
	ds_read_b64_tr_b16 v[212:213], v188 offset:0x800
	ds_read_b64_tr_b16 v[220:221], v188 offset:0x1000
	ds_read_b64_tr_b16 v[222:223], v188 offset:0x1800
	ds_read_b64_tr_b16 v[224:225], v188 offset:0x2000
	ds_read_b64_tr_b16 v[226:227], v188 offset:0x2800
	ds_read_b64_tr_b16 v[238:239], v188 offset:0x3000
	ds_read_b64_tr_b16 v[240:241], v188 offset:0x3800
	s_nop 0
	s_waitcnt lgkmcnt(6)
	v_mfma_f32_32x32x16_bf16 v[0:15], v[146:149], v[210:213], v[0:15]
	v_max_f32_e32 v230, v81, v81
	v_max_f32_e32 v231, v80, v80
	v_max_f32_e32 v230, v231, v230
	ds_read_b64_tr_b16 v[210:211], v188 offset:0x200
	ds_read_b64_tr_b16 v[212:213], v188 offset:0xa00
	s_waitcnt lgkmcnt(6)
	v_mfma_f32_32x32x16_bf16 v[0:15], v[206:209], v[220:223], v[0:15]
	v_max3_f32 v230, v230, v82, v83
	v_max3_f32 v230, v230, v84, v85
	v_max3_f32 v230, v230, v86, v87
	ds_read_b64_tr_b16 v[220:221], v188 offset:0x1200
	ds_read_b64_tr_b16 v[222:223], v188 offset:0x1a00
	s_waitcnt lgkmcnt(6)
	v_mfma_f32_32x32x16_bf16 v[0:15], v[152:155], v[224:227], v[0:15]
	v_max3_f32 v230, v230, v88, v89
	v_max3_f32 v230, v230, v90, v91
	v_max3_f32 v230, v230, v92, v93
	ds_read_b64_tr_b16 v[224:225], v188 offset:0x2200
	ds_read_b64_tr_b16 v[226:227], v188 offset:0x2a00
	s_waitcnt lgkmcnt(6)
	v_mfma_f32_32x32x16_bf16 v[0:15], v[156:159], v[238:241], v[0:15]
	v_max3_f32 v230, v230, v94, v95
	v_max3_f32 v230, v230, v64, v65
	v_max3_f32 v230, v230, v66, v67
	ds_read_b64_tr_b16 v[238:239], v188 offset:0x3200
	ds_read_b64_tr_b16 v[240:241], v188 offset:0x3a00
	s_waitcnt lgkmcnt(6)
	v_mfma_f32_32x32x16_bf16 v[48:63], v[146:149], v[210:213], v[48:63]
	v_max3_f32 v230, v230, v68, v69
	v_max3_f32 v230, v230, v70, v71
	v_max3_f32 v230, v230, v72, v73
	ds_read_b64_tr_b16 v[210:211], v188 offset:0x400
	ds_read_b64_tr_b16 v[212:213], v188 offset:0xc00
	s_waitcnt lgkmcnt(6)
	v_mfma_f32_32x32x16_bf16 v[48:63], v[206:209], v[220:223], v[48:63]
	v_max3_f32 v230, v230, v74, v75
	v_max3_f32 v230, v230, v76, v77
	v_max3_f32 v230, v230, v78, v79
	ds_read_b64_tr_b16 v[220:221], v188 offset:0x1400
	ds_read_b64_tr_b16 v[222:223], v188 offset:0x1c00
	s_waitcnt lgkmcnt(6)
	v_mfma_f32_32x32x16_bf16 v[48:63], v[152:155], v[224:227], v[48:63]
	v_mov_b32_e32 v231, v230
	s_nop 1
	v_permlane32_swap_b32_e32 v230, v231
	ds_read_b64_tr_b16 v[224:225], v188 offset:0x2400
	ds_read_b64_tr_b16 v[226:227], v188 offset:0x2c00
	s_waitcnt lgkmcnt(6)
	v_mfma_f32_32x32x16_bf16 v[48:63], v[156:159], v[238:241], v[48:63]
	v_max_f32_e32 v231, v231, v231
	v_max_f32_e32 v230, v230, v230
	v_max_f32_e32 v230, v230, v231
	ds_read_b64_tr_b16 v[238:239], v188 offset:0x3400
	ds_read_b64_tr_b16 v[240:241], v188 offset:0x3c00
	s_waitcnt lgkmcnt(6)
	v_mfma_f32_32x32x16_bf16 v[32:47], v[146:149], v[210:213], v[32:47]
	v_sub_f32_e32 v231, v230, v150
	v_mul_f32_e32 v231, 0x3db504f3, v231
	s_mov_b32 s6, 0x41000000
	ds_read_b64_tr_b16 v[210:211], v188 offset:0x600
	ds_read_b64_tr_b16 v[212:213], v188 offset:0xe00
	s_waitcnt lgkmcnt(6)
	v_mfma_f32_32x32x16_bf16 v[32:47], v[206:209], v[220:223], v[32:47]
	v_cmp_ge_f32_e32 vcc, s6, v231
	v_max_f32_e32 v231, v150, v150
	v_max_f32_e32 v230, v231, v230
	ds_read_b64_tr_b16 v[220:221], v188 offset:0x1600
	ds_read_b64_tr_b16 v[222:223], v188 offset:0x1e00
	s_waitcnt lgkmcnt(6)
	v_mfma_f32_32x32x16_bf16 v[32:47], v[152:155], v[224:227], v[32:47]
	v_sub_f32_e32 v231, v150, v230
	v_mul_f32_e32 v231, 0x3e0293ee, v231
	v_exp_f32_e32 v231, v231
	ds_read_b64_tr_b16 v[224:225], v188 offset:0x2600
	ds_read_b64_tr_b16 v[226:227], v188 offset:0x2e00
	s_waitcnt lgkmcnt(6)
	v_mfma_f32_32x32x16_bf16 v[32:47], v[156:159], v[238:241], v[32:47]
	ds_read_b64_tr_b16 v[238:239], v188 offset:0x3600
	ds_read_b64_tr_b16 v[240:241], v188 offset:0x3e00
	s_waitcnt lgkmcnt(6)
	v_mfma_f32_32x32x16_bf16 v[16:31], v[146:149], v[210:213], v[16:31]
	s_waitcnt lgkmcnt(4)
	v_mfma_f32_32x32x16_bf16 v[16:31], v[206:209], v[220:223], v[16:31]
	s_waitcnt lgkmcnt(2)
	v_mfma_f32_32x32x16_bf16 v[16:31], v[152:155], v[224:227], v[16:31]
	s_waitcnt lgkmcnt(0)
	v_mfma_f32_32x32x16_bf16 v[16:31], v[156:159], v[238:241], v[16:31]
	s_nop 0
	v_mov_b32_e32 v146, v230
	v_mov_b32_e32 v147, v231
	s_branch .Lpvj_1518a

.LBB0_1524:
	v_cndmask_b32_e64 v206, v146, v150, s[6:7]
	v_mul_f32_e32 v207, 0xbe0293ee, v206
	v_fmamk_f32 v80, v80, 0x3e0293ee, v207
	v_fmamk_f32 v81, v81, 0x3e0293ee, v207
	v_fmamk_f32 v82, v82, 0x3e0293ee, v207
	v_fmamk_f32 v83, v83, 0x3e0293ee, v207
	v_fmamk_f32 v84, v84, 0x3e0293ee, v207
	v_fmamk_f32 v85, v85, 0x3e0293ee, v207
	v_fmamk_f32 v86, v86, 0x3e0293ee, v207
	v_fmamk_f32 v87, v87, 0x3e0293ee, v207
	v_fmamk_f32 v88, v88, 0x3e0293ee, v207
	v_fmamk_f32 v89, v89, 0x3e0293ee, v207
	v_fmamk_f32 v90, v90, 0x3e0293ee, v207
	v_fmamk_f32 v91, v91, 0x3e0293ee, v207
	v_fmamk_f32 v92, v92, 0x3e0293ee, v207
	v_fmamk_f32 v93, v93, 0x3e0293ee, v207
	v_fmamk_f32 v94, v94, 0x3e0293ee, v207
	v_fmamk_f32 v95, v95, 0x3e0293ee, v207
	v_exp_f32_e32 v146, v80
	v_exp_f32_e32 v147, v81
	v_exp_f32_e32 v148, v82
	v_exp_f32_e32 v159, v83
	v_exp_f32_e32 v160, v84
	v_exp_f32_e32 v161, v85
	v_exp_f32_e32 v149, v86
	v_exp_f32_e32 v158, v87
	v_exp_f32_e32 v150, v88
	v_exp_f32_e32 v151, v89
	v_exp_f32_e32 v156, v90
	v_exp_f32_e32 v157, v91
	v_exp_f32_e32 v152, v92
	v_exp_f32_e32 v153, v93
	v_exp_f32_e32 v154, v94
	v_exp_f32_e32 v155, v95
	v_fmamk_f32 v209, v69, 0x3e0293ee, v207
	v_fmamk_f32 v208, v76, 0x3e0293ee, v207
	v_fmamk_f32 v222, v64, 0x3e0293ee, v207
	v_fmamk_f32 v224, v65, 0x3e0293ee, v207
	v_fmamk_f32 v225, v66, 0x3e0293ee, v207
	v_fmamk_f32 v226, v67, 0x3e0293ee, v207
	v_fmamk_f32 v227, v68, 0x3e0293ee, v207
	v_fmamk_f32 v210, v70, 0x3e0293ee, v207
	v_fmamk_f32 v211, v71, 0x3e0293ee, v207
	v_fmamk_f32 v212, v72, 0x3e0293ee, v207
	v_fmamk_f32 v213, v73, 0x3e0293ee, v207
	v_fmamk_f32 v218, v74, 0x3e0293ee, v207
	v_fmamk_f32 v220, v75, 0x3e0293ee, v207
	v_fmamk_f32 v228, v77, 0x3e0293ee, v207
	v_fmamk_f32 v238, v78, 0x3e0293ee, v207
	v_fmac_f32_e32 v207, 0x3e0293ee, v79
	s_waitcnt lgkmcnt(0)
	s_barrier
	v_mov_b32_e32 v234, v250
	v_mov_b32_e32 v235, v251
	ds_read_b128 v[80:83], v200 offset:256
	ds_read_b128 v[84:87], v200 offset:288
	ds_read_b128 v[64:67], v200 offset:384
	ds_read_b128 v[68:71], v200 offset:416
	ds_read_b128 v[88:91], v200 offset:320
	ds_read_b128 v[72:75], v200 offset:448
	ds_read_b128 v[92:95], v200 offset:352
	ds_read_b128 v[76:79], v200 offset:480
	ds_read_b128 v[244:247], v194 offset:32768
	ds_read_b128 v[240:243], v194 offset:40960
	ds_read_b128 v[248:251], v195 offset:32768
	v_exp_f32_e32 v221, v225
	v_exp_f32_e32 v225, v208
	v_add_f32_e32 v208, 0, v146
	s_waitcnt lgkmcnt(2)
	v_mfma_f32_32x32x16_bf16 v[80:95], v[244:247], v[126:129], v[80:95]
	ds_read_b128 v[244:247], v195 offset:40960
	v_add_f32_e32 v208, v147, v208
	v_add_f32_e32 v208, v148, v208
	v_add_f32_e32 v208, v159, v208
	v_add_f32_e32 v208, v160, v208
	v_add_f32_e32 v208, v161, v208
	v_add_f32_e32 v208, v149, v208
	v_add_f32_e32 v208, v158, v208
	s_waitcnt lgkmcnt(2)
	v_mfma_f32_32x32x16_bf16 v[64:79], v[240:243], v[126:129], v[64:79]
	ds_read_b128 v[240:243], v193 offset:32768
	v_add_f32_e32 v208, v150, v208
	v_add_f32_e32 v208, v151, v208
	v_add_f32_e32 v208, v156, v208
	v_add_f32_e32 v208, v157, v208
	v_exp_f32_e32 v214, v222
	v_add_f32_e32 v208, v152, v208
	s_waitcnt lgkmcnt(2)
	v_mfma_f32_32x32x16_bf16 v[80:95], v[248:251], v[122:125], v[80:95]
	ds_read_b128 v[248:251], v193 offset:40960
	v_exp_f32_e32 v215, v224
	v_add_f32_e32 v208, v153, v208
	v_add_f32_e32 v208, v154, v208
	v_exp_f32_e32 v222, v226
	v_add_f32_e32 v208, v155, v208
	v_exp_f32_e32 v223, v227
	v_add_f32_e32 v208, v214, v208
	s_waitcnt lgkmcnt(2)
	v_mfma_f32_32x32x16_bf16 v[64:79], v[244:247], v[122:125], v[64:79]
	ds_read_b128 v[244:247], v192 offset:32768
	v_exp_f32_e32 v224, v209
	v_add_f32_e32 v208, v215, v208
	v_exp_f32_e32 v210, v210
	v_add_f32_e32 v208, v221, v208
	v_exp_f32_e32 v211, v211
	v_add_f32_e32 v208, v222, v208
	s_waitcnt lgkmcnt(2)
	v_mfma_f32_32x32x16_bf16 v[80:95], v[240:243], v[118:121], v[80:95]
	ds_read_b128 v[240:243], v192 offset:40960
	v_exp_f32_e32 v212, v212
	v_add_f32_e32 v208, v223, v208
	v_exp_f32_e32 v213, v213
	v_add_f32_e32 v208, v224, v208
	v_exp_f32_e32 v218, v218
	v_add_f32_e32 v208, v210, v208
	v_exp_f32_e32 v220, v220
	s_waitcnt lgkmcnt(2)
	v_mfma_f32_32x32x16_bf16 v[64:79], v[248:251], v[118:121], v[64:79]
	ds_read_b128 v[248:251], v194 offset:32896
	v_add_f32_e32 v208, v211, v208
	v_add_f32_e32 v208, v212, v208
	v_exp_f32_e32 v226, v228
	v_add_f32_e32 v208, v213, v208
	v_exp_f32_e32 v227, v238
	v_add_f32_e32 v208, v218, v208
	s_waitcnt lgkmcnt(2)
	v_mfma_f32_32x32x16_bf16 v[80:95], v[244:247], v[114:117], v[80:95]
	ds_read_b128 v[244:247], v194 offset:41088
	v_exp_f32_e32 v207, v207
	v_add_f32_e32 v208, v220, v208
	v_add_f32_e32 v208, v225, v208
	v_add_f32_e32 v208, v226, v208
	v_add_f32_e32 v208, v227, v208
	v_add_f32_e32 v208, v207, v208
	v_mov_b32_e32 v209, v208
	s_waitcnt lgkmcnt(2)
	v_mfma_f32_32x32x16_bf16 v[64:79], v[240:243], v[114:117], v[64:79]
	ds_read_b128 v[240:243], v195 offset:32896
	v_cvt_pk_bf16_f32 v146, v146, v147
	v_cvt_pk_bf16_f32 v147, v148, v159
	v_cvt_pk_bf16_f32 v148, v160, v161
	v_cvt_pk_bf16_f32 v149, v149, v158
	v_cvt_pk_bf16_f32 v150, v150, v151
	v_cvt_pk_bf16_f32 v151, v156, v157
	s_waitcnt lgkmcnt(2)
	v_mfma_f32_32x32x16_bf16 v[80:95], v[248:251], v[110:113], v[80:95]
	ds_read_b128 v[248:251], v195 offset:41088
	v_cvt_pk_bf16_f32 v152, v152, v153
	v_cvt_pk_bf16_f32 v153, v154, v155
	v_cvt_pk_bf16_f32 v154, v214, v215
	v_cvt_pk_bf16_f32 v155, v221, v222
	v_cvt_pk_bf16_f32 v156, v223, v224
	v_cvt_pk_bf16_f32 v157, v210, v211
	v_cvt_pk_bf16_f32 v158, v212, v213
	s_waitcnt lgkmcnt(2)
	v_mfma_f32_32x32x16_bf16 v[64:79], v[244:247], v[110:113], v[64:79]
	ds_read_b128 v[244:247], v193 offset:32896
	v_cvt_pk_bf16_f32 v159, v218, v220
	v_cvt_pk_bf16_f32 v160, v225, v226
	v_cvt_pk_bf16_f32 v161, v227, v207
	v_permlane32_swap_b32_e32 v208, v209
	v_permlane32_swap_b32_e32 v146, v148
	s_waitcnt lgkmcnt(2)
	v_mfma_f32_32x32x16_bf16 v[80:95], v[240:243], v[106:109], v[80:95]
	ds_read_b128 v[240:243], v193 offset:41088
	v_permlane32_swap_b32_e32 v147, v149
	v_permlane32_swap_b32_e32 v150, v152
	v_permlane32_swap_b32_e32 v151, v153
	v_permlane32_swap_b32_e32 v154, v156
	s_waitcnt lgkmcnt(2)
	v_mfma_f32_32x32x16_bf16 v[64:79], v[248:251], v[106:109], v[64:79]
	ds_read_b128 v[248:251], v192 offset:32896
	v_permlane32_swap_b32_e32 v155, v157
	v_permlane32_swap_b32_e32 v158, v160
	v_permlane32_swap_b32_e32 v159, v161
	s_waitcnt lgkmcnt(2)
	v_mfma_f32_32x32x16_bf16 v[80:95], v[244:247], v[102:105], v[80:95]
	ds_read_b128 v[244:247], v192 offset:41088
	s_waitcnt lgkmcnt(2)
	v_mfma_f32_32x32x16_bf16 v[64:79], v[240:243], v[102:105], v[64:79]
	s_waitcnt lgkmcnt(1)
	v_mfma_f32_32x32x16_bf16 v[80:95], v[248:251], v[98:101], v[80:95]
	s_waitcnt lgkmcnt(0)
	v_mfma_f32_32x32x16_bf16 v[64:79], v[244:247], v[98:101], v[64:79]
	s_nop 1
	v_mov_b32_e32 v250, v234
	v_mov_b32_e32 v251, v235
	s_add_i32 s6, s80, 1
	v_readlane_b32 s7, v252, 43
	s_cmp_lt_i32 s6, s7
	s_cselect_b64 s[72:73], -1, 0
	s_cmp_ge_i32 s6, s7
	s_cbranch_scc1 .LBB0_1526
	v_lshl_add_u64 v[130:131], v[178:179], 0, v[96:97]
	v_lshl_add_u64 v[134:135], v[174:175], 0, v[96:97]
	v_lshl_add_u64 v[138:139], v[180:181], 0, v[96:97]
	v_lshl_add_u64 v[142:143], v[176:177], 0, v[96:97]
	global_load_dwordx4 v[130:133], v[130:131], off
	s_nop 0
	global_load_dwordx4 v[134:137], v[134:135], off
	s_nop 0
	global_load_dwordx4 v[138:141], v[138:139], off
	s_nop 0
	global_load_dwordx4 v[142:145], v[142:143], off
